# LN phases: wave reductions via DPP+readlane instead of ds_bpermute chains; next-row prefetch in plain LayerNorm loops
# speedup vs baseline: 1.0107x; 1.0032x over previous
.LBB0_303:
	s_add_i32 s4, s6, s8
	s_ashr_i32 s5, s4, 31
	s_lshl_b64 s[0:1], s[4:5], 12
	v_lshl_add_u64 v[64:65], v[152:153], 0, s[0:1]
	global_load_dwordx4 v[88:91], v[64:65], off offset:1024
	global_load_dwordx4 v[98:101], v[64:65], off offset:2048
	global_load_dwordx4 v[66:69], v[64:65], off offset:3072
	global_load_dwordx4 v[102:105], v[64:65], off
	v_mov_b32_e32 v200, v190
	v_mov_b32_e32 v201, v197
	s_mov_b32 s9, 0
	v_mov_b32_e32 v199, 0
	s_waitcnt vmcnt(3)
	v_lshlrev_b32_e32 v84, 16, v90
	s_waitcnt vmcnt(2)
	v_lshlrev_b32_e32 v78, 16, v98
	v_and_b32_e32 v82, 0xffff0000, v98
	v_lshlrev_b32_e32 v76, 16, v99
	v_and_b32_e32 v80, 0xffff0000, v99
	s_waitcnt vmcnt(0)
	v_lshlrev_b32_e32 v93, 16, v102
	v_lshlrev_b32_e32 v92, 16, v104
	v_and_b32_e32 v97, 0xffff0000, v102
	v_and_b32_e32 v96, 0xffff0000, v104
	v_lshlrev_b32_e32 v95, 16, v103
	v_lshlrev_b32_e32 v94, 16, v105
	v_and_b32_e32 v99, 0xffff0000, v103
	v_and_b32_e32 v98, 0xffff0000, v105
	v_and_b32_e32 v85, 0xffff0000, v90
	v_lshlrev_b32_e32 v86, 16, v91
	v_and_b32_e32 v87, 0xffff0000, v91
	v_lshlrev_b32_e32 v72, 16, v66
	v_and_b32_e32 v73, 0xffff0000, v66
	v_lshlrev_b32_e32 v74, 16, v67
	v_and_b32_e32 v75, 0xffff0000, v67
	v_lshlrev_b32_e32 v91, 16, v89
	v_lshlrev_b32_e32 v90, 16, v88
	v_and_b32_e32 v103, 0xffff0000, v89
	v_and_b32_e32 v102, 0xffff0000, v88
	v_pk_add_f32 v[104:105], v[92:93], v[96:97]
	v_pk_add_f32 v[106:107], v[94:95], v[98:99]
	v_lshlrev_b32_e32 v66, 16, v68
	v_and_b32_e32 v70, 0xffff0000, v68
	v_pk_add_f32 v[108:109], v[90:91], v[102:103]
	v_add_f32_e32 v67, v72, v73
	v_add_f32_e32 v71, v74, v75
	v_pk_add_f32 v[104:105], v[104:105], v[106:107]
	v_pk_add_f32 v[106:107], v[108:109], v[108:109] op_sel_hi:[0,1]
	v_pk_add_f32 v[112:113], v[66:67], v[70:71]
	v_add_f32_e32 v67, 0, v105
	v_add_f32_e32 v79, v84, v85
	v_add_f32_e32 v83, v86, v87
	v_mov_b32_e32 v77, v107
	v_add_f32_e32 v81, v104, v67
	v_lshlrev_b32_e32 v89, 16, v101
	v_lshlrev_b32_e32 v88, 16, v100
	v_and_b32_e32 v101, 0xffff0000, v101
	v_and_b32_e32 v100, 0xffff0000, v100
	v_pk_add_f32 v[108:109], v[78:79], v[82:83]
	v_pk_add_f32 v[104:105], v[76:77], v[80:81]
	v_pk_add_f32 v[110:111], v[88:89], v[100:101]
	v_pk_add_f32 v[104:105], v[108:109], v[104:105]
	v_pk_add_f32 v[110:111], v[110:111], v[110:111] op_sel_hi:[0,1]
	v_pk_add_f32 v[104:105], v[104:105], v[104:105] op_sel_hi:[0,1]
	v_lshlrev_b32_e32 v64, 16, v69
	v_and_b32_e32 v68, 0xffff0000, v69
	v_mov_b32_e32 v65, v111
	v_mov_b32_e32 v69, v105
	v_pk_add_f32 v[104:105], v[64:65], v[68:69]
	s_nop 0
	v_pk_add_f32 v[104:105], v[112:113], v[104:105]
	s_nop 0
	v_add_f32_e32 v65, v104, v105
	s_nop 1
	v_add_f32_dpp v65, v65, v65 quad_perm:[1,0,3,2] row_mask:0xf bank_mask:0xf
	s_nop 1
	v_add_f32_dpp v65, v65, v65 quad_perm:[2,3,0,1] row_mask:0xf bank_mask:0xf
	s_nop 1
	v_add_f32_dpp v65, v65, v65 row_half_mirror row_mask:0xf bank_mask:0xf
	s_nop 1
	v_add_f32_dpp v65, v65, v65 row_mirror row_mask:0xf bank_mask:0xf
	s_nop 1
	v_readlane_b32 s98, v65, 0
	v_readlane_b32 s99, v65, 16
	v_readlane_b32 s100, v65, 32
	v_readlane_b32 s101, v65, 48
	s_nop 1
	v_mov_b32_e32 v67, s98
	v_add_f32_e32 v67, s99, v67
	v_mov_b32_e32 v65, s100
	v_add_f32_e32 v65, s101, v65
	v_add_f32_e32 v65, v67, v65
	s_waitcnt lgkmcnt(0)
	v_fmac_f32_e32 v99, 0xba000000, v65
	v_fmac_f32_e32 v97, 0xba000000, v65
	v_fmac_f32_e32 v98, 0xba000000, v65
	v_fmac_f32_e32 v96, 0xba000000, v65
	v_fmac_f32_e32 v102, 0xba000000, v65
	v_fmac_f32_e32 v103, 0xba000000, v65
	v_fmac_f32_e32 v91, 0xba000000, v65
	v_fmac_f32_e32 v95, 0xba000000, v65
	v_fmac_f32_e32 v93, 0xba000000, v65
	v_fmac_f32_e32 v94, 0xba000000, v65
	v_fmac_f32_e32 v92, 0xba000000, v65
	v_fmac_f32_e32 v90, 0xba000000, v65
	v_fmac_f32_e32 v100, 0xba000000, v65
	v_fmac_f32_e32 v101, 0xba000000, v65
	v_fmac_f32_e32 v89, 0xba000000, v65
	v_mov_b32_e32 v106, v97
	v_mov_b32_e32 v107, v96
	v_mov_b32_e32 v110, v99
	v_mov_b32_e32 v111, v98
	v_mov_b32_e32 v112, v91
	v_mov_b32_e32 v113, v103
	v_mov_b32_e32 v91, v102
	v_mov_b32_e32 v104, v93
	v_mov_b32_e32 v105, v92
	v_mov_b32_e32 v108, v95
	v_mov_b32_e32 v109, v94
	v_mov_b32_e32 v116, v89
	v_mov_b32_e32 v117, v101
	v_mov_b32_e32 v89, v100
	v_pk_mul_f32 v[100:101], v[106:107], v[106:107]
	v_pk_mul_f32 v[106:107], v[110:111], v[110:111]
	v_pk_mul_f32 v[110:111], v[112:113], v[112:113]
	v_pk_mul_f32 v[118:119], v[90:91], v[90:91]
	v_fmac_f32_e32 v84, 0xba000000, v65
	v_fmac_f32_e32 v86, 0xba000000, v65
	v_pk_fma_f32 v[100:101], v[104:105], v[104:105], v[100:101]
	v_pk_fma_f32 v[104:105], v[108:109], v[108:109], v[106:107]
	v_pk_mov_b32 v[106:107], v[118:119], v[110:111] op_sel:[1,0]
	v_mov_b32_e32 v119, v111
	v_fmac_f32_e32 v85, 0xba000000, v65
	v_fmac_f32_e32 v87, 0xba000000, v65
	v_mul_f32_e32 v102, v84, v84
	v_mul_f32_e32 v114, v86, v86
	v_pk_add_f32 v[100:101], v[100:101], v[104:105]
	v_pk_add_f32 v[104:105], v[106:107], v[118:119]
	v_fmac_f32_e32 v80, 0xba000000, v65
	v_fmac_f32_e32 v76, 0xba000000, v65
	v_fmac_f32_e32 v82, 0xba000000, v65
	v_fmac_f32_e32 v78, 0xba000000, v65
	v_pk_fma_f32 v[102:103], v[84:85], v[84:85], v[102:103] op_sel_hi:[1,1,0]
	v_pk_fma_f32 v[114:115], v[86:87], v[86:87], v[114:115] op_sel_hi:[1,1,0]
	v_pk_add_f32 v[100:101], v[100:101], v[100:101] op_sel_hi:[0,1]
	v_pk_add_f32 v[104:105], v[104:105], v[104:105] op_sel_hi:[0,1]
	v_mul_f32_e32 v102, v78, v78
	v_mul_f32_e32 v114, v82, v82
	v_mul_f32_e32 v104, v76, v76
	v_mul_f32_e32 v100, v80, v80
	v_pk_add_f32 v[102:103], v[102:103], v[114:115]
	v_pk_add_f32 v[100:101], v[104:105], v[100:101]
	v_fmac_f32_e32 v88, 0xba000000, v65
	v_pk_add_f32 v[100:101], v[102:103], v[100:101]
	v_pk_mul_f32 v[120:121], v[116:117], v[116:117]
	v_pk_mul_f32 v[122:123], v[88:89], v[88:89]
	v_pk_add_f32 v[100:101], v[100:101], v[100:101] op_sel_hi:[0,1]
	v_fmac_f32_e32 v72, 0xba000000, v65
	v_pk_mov_b32 v[108:109], v[122:123], v[120:121] op_sel:[1,0]
	v_mov_b32_e32 v123, v121
	v_fmac_f32_e32 v73, 0xba000000, v65
	v_fmac_f32_e32 v74, 0xba000000, v65
	v_mul_f32_e32 v100, v72, v72
	v_pk_add_f32 v[102:103], v[108:109], v[122:123]
	v_fmac_f32_e32 v75, 0xba000000, v65
	v_pk_fma_f32 v[104:105], v[72:73], v[72:73], v[100:101] op_sel_hi:[1,1,0]
	v_mul_f32_e32 v100, v74, v74
	v_pk_add_f32 v[102:103], v[102:103], v[102:103] op_sel_hi:[0,1]
	v_pk_fma_f32 v[106:107], v[74:75], v[74:75], v[100:101] op_sel_hi:[1,1,0]
	v_fmac_f32_e32 v68, 0xba000000, v65
	v_fmac_f32_e32 v64, 0xba000000, v65
	v_fmac_f32_e32 v70, 0xba000000, v65
	v_fmac_f32_e32 v66, 0xba000000, v65
	v_mul_f32_e32 v104, v66, v66
	v_mul_f32_e32 v106, v70, v70
	v_mul_f32_e32 v102, v64, v64
	v_mul_f32_e32 v100, v68, v68
	v_pk_add_f32 v[104:105], v[104:105], v[106:107]
	v_pk_add_f32 v[100:101], v[102:103], v[100:101]
	v_mov_b32_e32 v102, v92
	v_pk_add_f32 v[100:101], v[104:105], v[100:101]
	v_mov_b32_e32 v103, v96
	v_add_f32_e32 v65, v100, v101
	v_mov_b32_e32 v96, v93
	v_mov_b32_e32 v92, v94
	v_mov_b32_e32 v93, v98
	v_mov_b32_e32 v98, v95
	v_mov_b32_e32 v79, v82
	v_mov_b32_e32 v77, v80
	v_lshl_add_u64 v[100:101], v[154:155], 0, s[0:1]
	s_nop 1
	v_add_f32_dpp v65, v65, v65 quad_perm:[1,0,3,2] row_mask:0xf bank_mask:0xf
	s_nop 1
	v_add_f32_dpp v65, v65, v65 quad_perm:[2,3,0,1] row_mask:0xf bank_mask:0xf
	s_nop 1
	v_add_f32_dpp v65, v65, v65 row_half_mirror row_mask:0xf bank_mask:0xf
	s_nop 1
	v_add_f32_dpp v65, v65, v65 row_mirror row_mask:0xf bank_mask:0xf
	s_nop 1
	v_readlane_b32 s98, v65, 0
	v_readlane_b32 s99, v65, 16
	v_readlane_b32 s100, v65, 32
	v_readlane_b32 s101, v65, 48
	s_nop 1
	v_mov_b32_e32 v67, s98
	v_add_f32_e32 v67, s99, v67
	v_mov_b32_e32 v65, s100
	v_add_f32_e32 v65, s101, v65
	v_add_f32_e32 v65, v67, v65
	s_waitcnt lgkmcnt(0)
	v_fmamk_f32 v65, v65, 0x3a000000, v198
	v_rsq_f32_e32 v104, v65
	v_mov_b32_e32 v67, v70
	v_mov_b32_e32 v65, v68
	v_pk_mul_f32 v[94:95], v[96:97], v[104:105] op_sel_hi:[1,0]
	v_pk_mul_f32 v[96:97], v[98:99], v[104:105] op_sel_hi:[1,0]
	v_pk_mul_f32 v[92:93], v[92:93], v[104:105] op_sel_hi:[1,0]
	v_pk_fma_f32 v[96:97], v[6:7], v[96:97], v[14:15]
	v_pk_fma_f32 v[98:99], v[4:5], v[94:95], v[12:13]
	v_pk_mul_f32 v[94:95], v[102:103], v[104:105] op_sel_hi:[1,0]
	v_pk_fma_f32 v[158:159], v[2:3], v[92:93], v[10:11]
	v_cvt_pk_bf16_f32 v92, v98, v99
	v_cvt_pk_bf16_f32 v93, v96, v97
	v_pk_mul_f32 v[78:79], v[78:79], v[104:105] op_sel_hi:[1,0]
	v_pk_mul_f32 v[76:77], v[76:77], v[104:105] op_sel_hi:[1,0]
	v_pk_fma_f32 v[160:161], v[0:1], v[94:95], v[8:9]
	v_pk_mul_f32 v[90:91], v[90:91], v[104:105] op_sel_hi:[1,0]
	v_cvt_pk_bf16_f32 v94, v160, v161
	v_cvt_pk_bf16_f32 v95, v158, v159
	global_store_dwordx4 v[100:101], v[92:95], off
	v_pk_mul_f32 v[84:85], v[84:85], v[104:105] op_sel_hi:[1,0]
	v_pk_mul_f32 v[86:87], v[86:87], v[104:105] op_sel_hi:[1,0]
	v_pk_mul_f32 v[92:93], v[112:113], v[104:105] op_sel_hi:[1,0]
	v_pk_fma_f32 v[80:81], v[34:35], v[76:77], v[42:43]
	v_pk_fma_f32 v[82:83], v[32:33], v[78:79], v[40:41]
	v_pk_mul_f32 v[76:77], v[88:89], v[104:105] op_sel_hi:[1,0]
	v_pk_mul_f32 v[78:79], v[116:117], v[104:105] op_sel_hi:[1,0]
	v_pk_mul_f32 v[72:73], v[72:73], v[104:105] op_sel_hi:[1,0]
	v_pk_mul_f32 v[74:75], v[74:75], v[104:105] op_sel_hi:[1,0]
	v_pk_mul_f32 v[66:67], v[66:67], v[104:105] op_sel_hi:[1,0]
	v_pk_mul_f32 v[64:65], v[64:65], v[104:105] op_sel_hi:[1,0]
	v_pk_fma_f32 v[92:93], v[22:23], v[92:93], v[30:31]
	v_pk_fma_f32 v[90:91], v[20:21], v[90:91], v[28:29]
	v_pk_fma_f32 v[162:163], v[18:19], v[86:87], v[26:27]
	v_pk_fma_f32 v[164:165], v[16:17], v[84:85], v[24:25]
	v_pk_fma_f32 v[166:167], v[38:39], v[78:79], v[46:47]
	v_pk_fma_f32 v[168:169], v[36:37], v[76:77], v[44:45]
	v_pk_fma_f32 v[74:75], v[50:51], v[74:75], v[58:59]
	v_pk_fma_f32 v[72:73], v[48:49], v[72:73], v[56:57]
	v_pk_fma_f32 v[170:171], v[54:55], v[64:65], v[62:63]
	v_pk_fma_f32 v[172:173], v[52:53], v[66:67], v[60:61]
	v_cvt_pk_bf16_f32 v84, v90, v91
	v_cvt_pk_bf16_f32 v85, v92, v93
	v_cvt_pk_bf16_f32 v86, v164, v165
	v_cvt_pk_bf16_f32 v87, v162, v163
	global_store_dwordx4 v[100:101], v[84:87], off offset:1024
	v_cvt_pk_bf16_f32 v76, v82, v83
	v_cvt_pk_bf16_f32 v77, v80, v81
	v_cvt_pk_bf16_f32 v78, v168, v169
	v_cvt_pk_bf16_f32 v79, v166, v167
	global_store_dwordx4 v[100:101], v[76:79], off offset:2048
	v_cvt_pk_bf16_f32 v64, v72, v73
	v_cvt_pk_bf16_f32 v65, v74, v75
	v_cvt_pk_bf16_f32 v66, v172, v173
	v_cvt_pk_bf16_f32 v67, v170, v171
	v_mov_b32_e32 v174, v98
	v_mov_b32_e32 v175, v160
	v_mov_b32_e32 v160, v99
	v_mov_b32_e32 v176, v96
	v_mov_b32_e32 v177, v158
	v_mov_b32_e32 v158, v97
	v_mov_b32_e32 v178, v90
	v_mov_b32_e32 v179, v164
	v_mov_b32_e32 v164, v91
	v_mov_b32_e32 v180, v92
	v_mov_b32_e32 v181, v162
	v_mov_b32_e32 v162, v93
	v_mov_b32_e32 v182, v82
	v_mov_b32_e32 v183, v168
	v_mov_b32_e32 v168, v83
	v_mov_b32_e32 v184, v80
	v_mov_b32_e32 v185, v166
	v_mov_b32_e32 v166, v81
	v_mov_b32_e32 v186, v72
	v_mov_b32_e32 v187, v172
	v_mov_b32_e32 v172, v73
	v_mov_b32_e32 v188, v74
	v_mov_b32_e32 v189, v170
	v_mov_b32_e32 v170, v75
	global_store_dwordx4 v[100:101], v[64:67], off offset:3072

.LBB0_953:
	s_cmp_lt_i32 s68, 11
	s_cselect_b64 s[4:5], -1, 0
	s_and_b64 s[0:1], s[4:5], s[0:1]
	s_andn2_b64 vcc, exec, s[0:1]
	s_cbranch_vccnz .LBB0_957
	s_lshl_b32 s8, s2, 3
	s_and_b32 s0, s34, 7
	s_and_b32 s9, s2, -8
	s_cmp_eq_u32 s0, 0
	s_cselect_b64 s[0:1], -1, 0
	s_movk_i32 s3, 0x800
	s_and_b64 s[6:7], s[0:1], exec
	v_mbcnt_hi_u32_b32 v67, -1, v212
	s_cselect_b32 s3, s3, 0x4000
	s_cselect_b32 s10, s9, s8
	s_add_i32 s6, 0, 0x23fd8
	v_add_u32_e32 v66, s94, v67
	v_mov_b32_e32 v0, s6
	ds_read_b32 v1, v0
	s_add_i32 s6, 0, 0x23fdc
	v_mov_b32_e32 v2, s6
	s_add_i32 s6, 0, 0x23f10
	ds_read_b32 v3, v2
	v_mov_b32_e32 v4, s6
	s_add_i32 s7, 0, 0x23f14
	ds_read_b32 v4, v4
	s_waitcnt lgkmcnt(0)
	v_readfirstlane_b32 s12, v1
	v_mov_b32_e32 v1, s7
	ds_read_b32 v1, v1
	s_add_i32 s7, 0, 0x23f18
	v_readfirstlane_b32 s6, v66
	v_readfirstlane_b32 s13, v3
	v_mov_b32_e32 v3, s7
	s_add_i32 s7, 0, 0x23f1c
	s_ashr_i32 s11, s6, 6
	v_readfirstlane_b32 s6, v4
	v_mov_b32_e32 v4, s7
	ds_read_b32 v3, v3
	ds_read_b32 v4, v4
	ds_read_b32 v0, v0
	s_waitcnt lgkmcnt(0)
	v_readfirstlane_b32 s7, v1
	ds_read_b32 v1, v2
	s_add_i32 s14, s11, s10
	v_readfirstlane_b32 s8, v3
	v_readfirstlane_b32 s9, v4
	v_readfirstlane_b32 s15, v0
	s_cmp_ge_i32 s14, s3
	s_waitcnt lgkmcnt(0)
	v_readfirstlane_b32 s16, v1
	s_cbranch_scc1 .LBB0_957
	v_lshlrev_b32_e32 v0, 5, v66
	v_and_b32_e32 v64, 0x7e0, v0
	v_mov_b32_e32 v65, 0
	v_lshl_add_u64 v[48:49], s[6:7], 0, v[64:65]
	s_mov_b64 s[6:7], 0x2000
	v_lshl_add_u64 v[56:57], s[8:9], 0, v[64:65]
	v_lshl_add_u64 v[24:25], v[48:49], 0, s[6:7]
	v_lshl_add_u64 v[26:27], v[56:57], 0, s[6:7]
	s_movk_i32 s6, 0x3000
	v_add_co_u32_e32 v58, vcc, s6, v48
	global_load_dwordx4 v[0:3], v[24:25], off offset:2064
	global_load_dwordx4 v[4:7], v[24:25], off offset:16
	global_load_dwordx4 v[8:11], v[24:25], off offset:2048
	global_load_dwordx4 v[12:15], v[26:27], off offset:2064
	global_load_dwordx4 v[16:19], v[26:27], off offset:16
	global_load_dwordx4 v[20:23], v[26:27], off offset:2048
	v_addc_co_u32_e32 v59, vcc, 0, v49, vcc
	v_add_co_u32_e32 v68, vcc, s6, v56
	s_mov_b64 s[6:7], 0x3000
	s_nop 0
	v_addc_co_u32_e32 v69, vcc, 0, v57, vcc
	v_lshl_add_u64 v[36:37], v[48:49], 0, s[6:7]
	v_lshl_add_u64 v[50:51], v[56:57], 0, s[6:7]
	s_mov_b64 s[6:7], 0x3800
	global_load_dwordx4 v[24:27], v[58:59], off offset:-4096
	global_load_dwordx4 v[28:31], v[58:59], off
	global_load_dwordx4 v[32:35], v[36:37], off offset:16
	s_nop 0
	global_load_dwordx4 v[36:39], v[68:69], off offset:-4096
	global_load_dwordx4 v[40:43], v[68:69], off
	global_load_dwordx4 v[44:47], v[50:51], off offset:16
	v_lshl_add_u64 v[60:61], v[48:49], 0, s[6:7]
	global_load_dwordx4 v[48:51], v[58:59], off offset:2048
	global_load_dwordx4 v[52:55], v[60:61], off offset:16
	v_lshl_add_u64 v[70:71], v[56:57], 0, s[6:7]
	global_load_dwordx4 v[56:59], v[68:69], off offset:2048
	global_load_dwordx4 v[60:63], v[70:71], off offset:16
	s_lshl_b32 s8, s34, 3
	s_and_b64 s[6:7], s[0:1], exec
	s_cselect_b32 s6, s34, s8
	s_lshl_b32 s7, s2, 11
	s_and_b32 s7, s7, 0x3800
	s_and_b64 s[0:1], s[0:1], exec
	v_and_b32_e32 v64, 64, v67
	s_cselect_b32 s0, s7, 0
	v_add_u32_e32 v64, 64, v64
	v_xor_b32_e32 v68, 1, v67
	v_cmp_lt_i32_e32 vcc, v68, v64
	v_xor_b32_e32 v69, 2, v67
	s_add_i32 s0, s10, s0
	v_cndmask_b32_e32 v68, v67, v68, vcc
	v_cmp_lt_i32_e32 vcc, v69, v64
	v_xor_b32_e32 v70, 4, v67
	s_add_i32 s0, s0, s11
	v_cndmask_b32_e32 v69, v67, v69, vcc
	v_cmp_lt_i32_e32 vcc, v70, v64
	v_xor_b32_e32 v71, 8, v67
	s_ashr_i32 s1, s0, 31
	v_cndmask_b32_e32 v70, v67, v70, vcc
	v_cmp_lt_i32_e32 vcc, v71, v64
	v_xor_b32_e32 v72, 16, v67
	s_lshl_b64 s[0:1], s[0:1], 12
	v_cndmask_b32_e32 v71, v67, v71, vcc
	v_cmp_lt_i32_e32 vcc, v72, v64
	v_xor_b32_e32 v73, 32, v67
	s_add_u32 s8, s15, s0
	v_cndmask_b32_e32 v72, v67, v72, vcc
	v_cmp_lt_i32_e32 vcc, v73, v64
	s_addc_u32 s9, s16, s1
	s_ashr_i32 s7, s6, 31
	v_cndmask_b32_e32 v64, v67, v73, vcc
	s_lshl_b64 s[10:11], s[6:7], 12
	v_lshlrev_b32_e32 v73, 2, v64
	v_and_b32_e32 v64, 63, v66
	s_add_u32 s12, s12, s0
	v_lshlrev_b32_e32 v68, 2, v68
	v_lshlrev_b32_e32 v69, 2, v69
	v_lshlrev_b32_e32 v70, 2, v70
	v_lshlrev_b32_e32 v71, 2, v71
	v_lshlrev_b32_e32 v72, 2, v72
	v_lshlrev_b32_e32 v64, 4, v64
	s_addc_u32 s13, s13, s1
	v_mov_b32_e32 v74, 0x3727c5ac
	s_mov_b32 s7, 0x1da00000
	s_mov_b64 s[22:23], 0x21a00000
	v_lshl_add_u64 v[156:157], s[12:13], 0, v[64:65]
	v_lshl_add_u64 v[156:157], v[156:157], 0, s[22:23]
	global_load_dwordx4 v[140:143], v[156:157], off offset:1024
	global_load_dwordx4 v[144:147], v[156:157], off offset:2048
	global_load_dwordx4 v[148:151], v[156:157], off offset:3072
	global_load_dwordx4 v[152:155], v[156:157], off
	s_waitcnt vmcnt(0)
.LBB0_956:
	v_lshl_add_u64 v[66:67], s[12:13], 0, v[64:65]
	v_lshl_add_u64 v[76:77], s[8:9], 0, v[64:65]
	v_add_co_u32_e32 v66, vcc, 0x21a00000, v66
	v_add_co_u32_e64 v92, s[0:1], s7, v76
	s_nop 0
	v_addc_co_u32_e32 v67, vcc, 0, v67, vcc
	v_addc_co_u32_e64 v93, s[0:1], 0, v77, s[0:1]
	s_waitcnt vmcnt(4)
	v_mov_b32_e32 v76, v140
	v_mov_b32_e32 v77, v141
	v_mov_b32_e32 v78, v142
	v_mov_b32_e32 v79, v143
	v_mov_b32_e32 v80, v144
	v_mov_b32_e32 v81, v145
	v_mov_b32_e32 v82, v146
	v_mov_b32_e32 v83, v147
	v_mov_b32_e32 v84, v148
	v_mov_b32_e32 v85, v149
	v_mov_b32_e32 v86, v150
	v_mov_b32_e32 v87, v151
	v_mov_b32_e32 v88, v152
	v_mov_b32_e32 v89, v153
	v_mov_b32_e32 v90, v154
	v_mov_b32_e32 v91, v155
	s_add_i32 s14, s14, s6
	s_add_u32 s8, s8, s10
	s_addc_u32 s9, s9, s11
	s_add_u32 s12, s12, s10
	s_addc_u32 s13, s13, s11
	s_cmp_lt_i32 s14, s3
	v_lshl_add_u64 v[156:157], s[12:13], 0, v[64:65]
	v_lshl_add_u64 v[156:157], v[156:157], 0, s[22:23]
	global_load_dwordx4 v[140:143], v[156:157], off offset:1024
	global_load_dwordx4 v[144:147], v[156:157], off offset:2048
	global_load_dwordx4 v[148:151], v[156:157], off offset:3072
	global_load_dwordx4 v[152:155], v[156:157], off
	v_lshlrev_b32_e32 v66, 16, v78
	v_and_b32_e32 v67, 0xffff0000, v78
	v_lshlrev_b32_e32 v78, 16, v79
	v_lshlrev_b32_e32 v109, 16, v88
	v_lshlrev_b32_e32 v108, 16, v90
	v_and_b32_e32 v111, 0xffff0000, v88
	v_and_b32_e32 v110, 0xffff0000, v90
	v_lshlrev_b32_e32 v113, 16, v89
	v_lshlrev_b32_e32 v112, 16, v91
	v_and_b32_e32 v89, 0xffff0000, v89
	v_and_b32_e32 v88, 0xffff0000, v91
	v_lshlrev_b32_e32 v91, 16, v77
	v_lshlrev_b32_e32 v90, 16, v76
	v_and_b32_e32 v77, 0xffff0000, v77
	v_and_b32_e32 v76, 0xffff0000, v76
	v_pk_add_f32 v[116:117], v[108:109], v[110:111]
	v_pk_add_f32 v[118:119], v[112:113], v[88:89]
	v_pk_add_f32 v[120:121], v[90:91], v[76:77]
	v_pk_add_f32 v[116:117], v[116:117], v[118:119]
	v_and_b32_e32 v79, 0xffff0000, v79
	v_pk_add_f32 v[118:119], v[120:121], v[120:121] op_sel_hi:[0,1]
	v_add_f32_e32 v75, 0, v117
	v_lshlrev_b32_e32 v94, 16, v80
	v_and_b32_e32 v80, 0xffff0000, v80
	v_lshlrev_b32_e32 v96, 16, v81
	v_and_b32_e32 v98, 0xffff0000, v81
	v_add_f32_e32 v95, v66, v67
	v_add_f32_e32 v81, v78, v79
	v_mov_b32_e32 v97, v119
	v_add_f32_e32 v99, v116, v75
	v_lshlrev_b32_e32 v115, 16, v83
	v_lshlrev_b32_e32 v114, 16, v82
	v_and_b32_e32 v83, 0xffff0000, v83
	v_and_b32_e32 v82, 0xffff0000, v82
	v_pk_add_f32 v[120:121], v[94:95], v[80:81]
	v_pk_add_f32 v[116:117], v[96:97], v[98:99]
	v_pk_add_f32 v[122:123], v[114:115], v[82:83]
	v_pk_add_f32 v[116:117], v[120:121], v[116:117]
	v_lshlrev_b32_e32 v100, 16, v84
	v_and_b32_e32 v101, 0xffff0000, v84
	v_lshlrev_b32_e32 v84, 16, v85
	v_and_b32_e32 v85, 0xffff0000, v85
	v_pk_add_f32 v[122:123], v[122:123], v[122:123] op_sel_hi:[0,1]
	v_pk_add_f32 v[116:117], v[116:117], v[116:117] op_sel_hi:[0,1]
	v_lshlrev_b32_e32 v102, 16, v86
	v_and_b32_e32 v86, 0xffff0000, v86
	v_lshlrev_b32_e32 v104, 16, v87
	v_and_b32_e32 v106, 0xffff0000, v87
	v_add_f32_e32 v103, v100, v101
	v_add_f32_e32 v87, v84, v85
	v_mov_b32_e32 v105, v123
	v_mov_b32_e32 v107, v117
	v_pk_add_f32 v[124:125], v[102:103], v[86:87]
	v_pk_add_f32 v[116:117], v[104:105], v[106:107]
	s_nop 0
	v_pk_add_f32 v[116:117], v[124:125], v[116:117]
	s_nop 0
	v_add_f32_e32 v75, v116, v117
	s_nop 1
	v_add_f32_dpp v75, v75, v75 quad_perm:[1,0,3,2] row_mask:0xf bank_mask:0xf
	s_nop 1
	v_add_f32_dpp v75, v75, v75 quad_perm:[2,3,0,1] row_mask:0xf bank_mask:0xf
	s_nop 1
	v_add_f32_dpp v75, v75, v75 row_half_mirror row_mask:0xf bank_mask:0xf
	s_nop 1
	v_add_f32_dpp v75, v75, v75 row_mirror row_mask:0xf bank_mask:0xf
	s_nop 1
	v_readlane_b32 s98, v75, 0
	v_readlane_b32 s99, v75, 16
	v_readlane_b32 s100, v75, 32
	v_readlane_b32 s101, v75, 48
	s_nop 1
	v_mov_b32_e32 v81, s98
	v_add_f32_e32 v81, s99, v81
	v_mov_b32_e32 v75, s100
	v_add_f32_e32 v75, s101, v75
	v_add_f32_e32 v75, v81, v75
	s_waitcnt lgkmcnt(0)
	v_fmac_f32_e32 v89, 0xba000000, v75
	v_fmac_f32_e32 v113, 0xba000000, v75
	v_fmac_f32_e32 v111, 0xba000000, v75
	v_fmac_f32_e32 v109, 0xba000000, v75
	v_fmac_f32_e32 v88, 0xba000000, v75
	v_fmac_f32_e32 v112, 0xba000000, v75
	v_fmac_f32_e32 v110, 0xba000000, v75
	v_fmac_f32_e32 v108, 0xba000000, v75
	v_fmac_f32_e32 v76, 0xba000000, v75
	v_fmac_f32_e32 v77, 0xba000000, v75
	v_fmac_f32_e32 v91, 0xba000000, v75
	v_fmac_f32_e32 v90, 0xba000000, v75
	v_fmac_f32_e32 v84, 0xba000000, v75
	v_mov_b32_e32 v116, v108
	v_mov_b32_e32 v117, v110
	v_mov_b32_e32 v118, v109
	v_mov_b32_e32 v119, v111
	v_mov_b32_e32 v120, v109
	v_mov_b32_e32 v121, v108
	v_mov_b32_e32 v108, v111
	v_mov_b32_e32 v109, v110
	v_mov_b32_e32 v110, v112
	v_mov_b32_e32 v111, v88
	v_mov_b32_e32 v122, v113
	v_mov_b32_e32 v123, v89
	v_mov_b32_e32 v124, v113
	v_mov_b32_e32 v125, v112
	v_mov_b32_e32 v112, v89
	v_mov_b32_e32 v113, v88
	v_mov_b32_e32 v88, v91
	v_mov_b32_e32 v89, v77
	v_mov_b32_e32 v91, v76
	v_fmac_f32_e32 v85, 0xba000000, v75
	v_mul_f32_e32 v130, v84, v84
	v_pk_mul_f32 v[108:109], v[108:109], v[108:109]
	v_pk_mul_f32 v[112:113], v[112:113], v[112:113]
	v_pk_mul_f32 v[132:133], v[88:89], v[88:89]
	v_pk_mul_f32 v[134:135], v[90:91], v[90:91]
	v_fmac_f32_e32 v66, 0xba000000, v75
	v_fmac_f32_e32 v78, 0xba000000, v75
	v_fmac_f32_e32 v86, 0xba000000, v75
	v_pk_fma_f32 v[130:131], v[84:85], v[84:85], v[130:131] op_sel_hi:[1,1,0]
	v_pk_fma_f32 v[108:109], v[120:121], v[120:121], v[108:109]
	v_pk_fma_f32 v[112:113], v[124:125], v[124:125], v[112:113]
	v_pk_mov_b32 v[120:121], v[134:135], v[132:133] op_sel:[1,0]
	v_mov_b32_e32 v135, v133
	v_fmac_f32_e32 v67, 0xba000000, v75
	v_fmac_f32_e32 v79, 0xba000000, v75
	v_fmac_f32_e32 v82, 0xba000000, v75
	v_fmac_f32_e32 v83, 0xba000000, v75
	v_fmac_f32_e32 v115, 0xba000000, v75
	v_mul_f32_e32 v76, v66, v66
	v_mul_f32_e32 v126, v78, v78
	v_mov_b32_e32 v103, v86
	v_mul_f32_e32 v130, v86, v86
	v_pk_add_f32 v[86:87], v[108:109], v[112:113]
	v_pk_add_f32 v[108:109], v[120:121], v[134:135]
	v_fmac_f32_e32 v98, 0xba000000, v75
	v_fmac_f32_e32 v96, 0xba000000, v75
	v_fmac_f32_e32 v80, 0xba000000, v75
	v_fmac_f32_e32 v94, 0xba000000, v75
	v_fmac_f32_e32 v114, 0xba000000, v75
	v_mov_b32_e32 v128, v115
	v_mov_b32_e32 v129, v83
	v_mov_b32_e32 v115, v82
	v_pk_fma_f32 v[76:77], v[66:67], v[66:67], v[76:77] op_sel_hi:[1,1,0]
	v_pk_fma_f32 v[126:127], v[78:79], v[78:79], v[126:127] op_sel_hi:[1,1,0]
	v_pk_add_f32 v[86:87], v[86:87], v[86:87] op_sel_hi:[0,1]
	v_pk_add_f32 v[108:109], v[108:109], v[108:109] op_sel_hi:[0,1]
	v_pk_mul_f32 v[136:137], v[128:129], v[128:129]
	v_pk_mul_f32 v[138:139], v[114:115], v[114:115]
	v_mul_f32_e32 v76, v94, v94
	v_mul_f32_e32 v126, v80, v80
	v_mul_f32_e32 v108, v96, v96
	v_mul_f32_e32 v86, v98, v98
	v_fmac_f32_e32 v100, 0xba000000, v75
	v_mov_b32_e32 v95, v80
	v_pk_mov_b32 v[80:81], v[138:139], v[136:137] op_sel:[1,0]
	v_mov_b32_e32 v139, v137
	v_pk_add_f32 v[76:77], v[76:77], v[126:127]
	v_pk_add_f32 v[86:87], v[108:109], v[86:87]
	v_fmac_f32_e32 v101, 0xba000000, v75
	v_mul_f32_e32 v82, v100, v100
	v_pk_add_f32 v[80:81], v[80:81], v[138:139]
	v_pk_add_f32 v[76:77], v[76:77], v[86:87]
	v_fmac_f32_e32 v106, 0xba000000, v75
	v_fmac_f32_e32 v104, 0xba000000, v75
	v_fmac_f32_e32 v102, 0xba000000, v75
	v_pk_fma_f32 v[82:83], v[100:101], v[100:101], v[82:83] op_sel_hi:[1,1,0]
	v_pk_add_f32 v[80:81], v[80:81], v[80:81] op_sel_hi:[0,1]
	v_pk_add_f32 v[76:77], v[76:77], v[76:77] op_sel_hi:[0,1]
	v_mul_f32_e32 v82, v102, v102
	v_mul_f32_e32 v80, v104, v104
	v_mul_f32_e32 v76, v106, v106
	v_pk_add_f32 v[82:83], v[82:83], v[130:131]
	v_pk_add_f32 v[76:77], v[80:81], v[76:77]
	v_mov_b32_e32 v97, v98
	v_pk_add_f32 v[76:77], v[82:83], v[76:77]
	v_mov_b32_e32 v105, v106
	v_add_f32_e32 v75, v76, v77
	s_nop 1
	v_add_f32_dpp v75, v75, v75 quad_perm:[1,0,3,2] row_mask:0xf bank_mask:0xf
	s_nop 1
	v_add_f32_dpp v75, v75, v75 quad_perm:[2,3,0,1] row_mask:0xf bank_mask:0xf
	s_nop 1
	v_add_f32_dpp v75, v75, v75 row_half_mirror row_mask:0xf bank_mask:0xf
	s_nop 1
	v_add_f32_dpp v75, v75, v75 row_mirror row_mask:0xf bank_mask:0xf
	s_nop 1
	v_readlane_b32 s98, v75, 0
	v_readlane_b32 s99, v75, 16
	v_readlane_b32 s100, v75, 32
	v_readlane_b32 s101, v75, 48
	s_nop 1
	v_mov_b32_e32 v76, s98
	v_add_f32_e32 v76, s99, v76
	v_mov_b32_e32 v75, s100
	v_add_f32_e32 v75, s101, v75
	v_add_f32_e32 v75, v76, v75
	s_waitcnt lgkmcnt(0)
	v_fmamk_f32 v75, v75, 0x3a000000, v74
	v_rsq_f32_e32 v76, v75
	s_nop 0
	v_pk_mul_f32 v[80:81], v[118:119], v[76:77] op_sel_hi:[1,0]
	v_pk_mul_f32 v[82:83], v[122:123], v[76:77] op_sel_hi:[1,0]
	v_pk_mul_f32 v[86:87], v[116:117], v[76:77] op_sel_hi:[1,0]
	v_pk_mul_f32 v[98:99], v[110:111], v[76:77] op_sel_hi:[1,0]
	v_pk_mul_f32 v[90:91], v[90:91], v[76:77] op_sel_hi:[1,0]
	v_pk_mul_f32 v[88:89], v[88:89], v[76:77] op_sel_hi:[1,0]
	v_pk_mul_f32 v[66:67], v[66:67], v[76:77] op_sel_hi:[1,0]
	v_pk_mul_f32 v[78:79], v[78:79], v[76:77] op_sel_hi:[1,0]
	v_pk_mul_f32 v[94:95], v[94:95], v[76:77] op_sel_hi:[1,0]
	v_pk_mul_f32 v[96:97], v[96:97], v[76:77] op_sel_hi:[1,0]
	v_pk_mul_f32 v[106:107], v[114:115], v[76:77] op_sel_hi:[1,0]
	v_pk_mul_f32 v[108:109], v[128:129], v[76:77] op_sel_hi:[1,0]
	v_pk_mul_f32 v[100:101], v[100:101], v[76:77] op_sel_hi:[1,0]
	v_pk_mul_f32 v[84:85], v[84:85], v[76:77] op_sel_hi:[1,0]
	v_pk_mul_f32 v[102:103], v[102:103], v[76:77] op_sel_hi:[1,0]
	v_pk_mul_f32 v[76:77], v[104:105], v[76:77] op_sel_hi:[1,0]
	v_pk_fma_f32 v[82:83], v[26:27], v[82:83], v[38:39]
	v_pk_fma_f32 v[80:81], v[24:25], v[80:81], v[36:37]
	v_pk_fma_f32 v[98:99], v[6:7], v[98:99], v[18:19]
	v_pk_fma_f32 v[86:87], v[4:5], v[86:87], v[16:17]
	v_pk_fma_f32 v[104:105], v[2:3], v[78:79], v[14:15]
	v_pk_fma_f32 v[110:111], v[54:55], v[76:77], v[62:63]
	v_cvt_pk_bf16_f32 v76, v80, v81
	v_cvt_pk_bf16_f32 v77, v82, v83
	v_cvt_pk_bf16_f32 v78, v86, v87
	v_cvt_pk_bf16_f32 v79, v98, v99
	v_pk_fma_f32 v[88:89], v[10:11], v[88:89], v[22:23]
	v_pk_fma_f32 v[90:91], v[8:9], v[90:91], v[20:21]
	v_pk_fma_f32 v[66:67], v[0:1], v[66:67], v[12:13]
	global_store_dwordx4 v[92:93], v[76:79], off
	v_pk_fma_f32 v[96:97], v[30:31], v[96:97], v[42:43]
	v_pk_fma_f32 v[94:95], v[28:29], v[94:95], v[40:41]
	v_cvt_pk_bf16_f32 v76, v90, v91
	v_cvt_pk_bf16_f32 v77, v88, v89
	v_cvt_pk_bf16_f32 v78, v66, v67
	v_cvt_pk_bf16_f32 v79, v104, v105
	v_pk_fma_f32 v[108:109], v[34:35], v[108:109], v[46:47]
	v_pk_fma_f32 v[106:107], v[32:33], v[106:107], v[44:45]
	global_store_dwordx4 v[92:93], v[76:79], off offset:1024
	v_pk_fma_f32 v[84:85], v[50:51], v[84:85], v[58:59]
	v_pk_fma_f32 v[100:101], v[48:49], v[100:101], v[56:57]
	v_cvt_pk_bf16_f32 v76, v94, v95
	v_cvt_pk_bf16_f32 v77, v96, v97
	v_cvt_pk_bf16_f32 v78, v106, v107
	v_cvt_pk_bf16_f32 v79, v108, v109
	v_pk_fma_f32 v[102:103], v[52:53], v[102:103], v[60:61]
	global_store_dwordx4 v[92:93], v[76:79], off offset:2048
	s_nop 1
	v_cvt_pk_bf16_f32 v76, v100, v101
	v_cvt_pk_bf16_f32 v77, v84, v85
	v_cvt_pk_bf16_f32 v78, v102, v103
	v_cvt_pk_bf16_f32 v79, v110, v111
	global_store_dwordx4 v[92:93], v[76:79], off offset:3072
	s_cbranch_scc1 .LBB0_956

.LBB0_1167:
	s_cmp_lt_i32 s68, 14
	s_cselect_b64 s[4:5], -1, 0
	s_and_b64 s[0:1], s[4:5], s[0:1]
	s_andn2_b64 vcc, exec, s[0:1]
	s_cbranch_vccnz .LBB0_1171
	s_lshl_b32 s8, s2, 3
	s_and_b32 s0, s34, 7
	s_and_b32 s9, s2, -8
	s_cmp_eq_u32 s0, 0
	s_cselect_b64 s[0:1], -1, 0
	s_movk_i32 s3, 0x800
	s_and_b64 s[6:7], s[0:1], exec
	v_mbcnt_hi_u32_b32 v67, -1, v212
	s_cselect_b32 s3, s3, 0x4000
	s_cselect_b32 s10, s9, s8
	s_add_i32 s6, 0, 0x23fd8
	v_add_u32_e32 v66, s94, v67
	v_mov_b32_e32 v0, s6
	ds_read_b32 v1, v0
	s_add_i32 s6, 0, 0x23fdc
	v_mov_b32_e32 v2, s6
	s_add_i32 s6, 0, 0x23f10
	ds_read_b32 v3, v2
	v_mov_b32_e32 v4, s6
	s_add_i32 s7, 0, 0x23f14
	ds_read_b32 v4, v4
	s_waitcnt lgkmcnt(0)
	v_readfirstlane_b32 s12, v1
	v_mov_b32_e32 v1, s7
	ds_read_b32 v1, v1
	s_add_i32 s7, 0, 0x23f18
	v_readfirstlane_b32 s6, v66
	v_readfirstlane_b32 s13, v3
	v_mov_b32_e32 v3, s7
	s_add_i32 s7, 0, 0x23f1c
	s_ashr_i32 s11, s6, 6
	v_readfirstlane_b32 s6, v4
	v_mov_b32_e32 v4, s7
	ds_read_b32 v3, v3
	ds_read_b32 v4, v4
	ds_read_b32 v0, v0
	s_waitcnt lgkmcnt(0)
	v_readfirstlane_b32 s7, v1
	ds_read_b32 v1, v2
	s_add_i32 s14, s11, s10
	v_readfirstlane_b32 s8, v3
	v_readfirstlane_b32 s9, v4
	v_readfirstlane_b32 s15, v0
	s_cmp_ge_i32 s14, s3
	s_waitcnt lgkmcnt(0)
	v_readfirstlane_b32 s16, v1
	s_cbranch_scc1 .LBB0_1171
	v_lshlrev_b32_e32 v0, 5, v66
	v_and_b32_e32 v64, 0x7e0, v0
	v_mov_b32_e32 v65, 0
	v_lshl_add_u64 v[48:49], s[6:7], 0, v[64:65]
	s_mov_b64 s[6:7], 0x4000
	v_lshl_add_u64 v[56:57], s[8:9], 0, v[64:65]
	v_lshl_add_u64 v[24:25], v[48:49], 0, s[6:7]
	v_lshl_add_u64 v[26:27], v[56:57], 0, s[6:7]
	s_movk_i32 s6, 0x5000
	v_add_co_u32_e32 v58, vcc, s6, v48
	global_load_dwordx4 v[0:3], v[24:25], off offset:2064
	global_load_dwordx4 v[4:7], v[24:25], off offset:16
	global_load_dwordx4 v[8:11], v[24:25], off offset:2048
	global_load_dwordx4 v[12:15], v[26:27], off offset:2064
	global_load_dwordx4 v[16:19], v[26:27], off offset:16
	global_load_dwordx4 v[20:23], v[26:27], off offset:2048
	v_addc_co_u32_e32 v59, vcc, 0, v49, vcc
	v_add_co_u32_e32 v68, vcc, s6, v56
	s_mov_b64 s[6:7], 0x5000
	s_nop 0
	v_addc_co_u32_e32 v69, vcc, 0, v57, vcc
	v_lshl_add_u64 v[36:37], v[48:49], 0, s[6:7]
	v_lshl_add_u64 v[50:51], v[56:57], 0, s[6:7]
	s_mov_b64 s[6:7], 0x5800
	global_load_dwordx4 v[24:27], v[58:59], off offset:-4096
	global_load_dwordx4 v[28:31], v[58:59], off
	global_load_dwordx4 v[32:35], v[36:37], off offset:16
	s_nop 0
	global_load_dwordx4 v[36:39], v[68:69], off offset:-4096
	global_load_dwordx4 v[40:43], v[68:69], off
	global_load_dwordx4 v[44:47], v[50:51], off offset:16
	v_lshl_add_u64 v[60:61], v[48:49], 0, s[6:7]
	global_load_dwordx4 v[48:51], v[58:59], off offset:2048
	global_load_dwordx4 v[52:55], v[60:61], off offset:16
	v_lshl_add_u64 v[70:71], v[56:57], 0, s[6:7]
	global_load_dwordx4 v[56:59], v[68:69], off offset:2048
	global_load_dwordx4 v[60:63], v[70:71], off offset:16
	s_lshl_b32 s8, s34, 3
	s_and_b64 s[6:7], s[0:1], exec
	s_cselect_b32 s6, s34, s8
	s_lshl_b32 s7, s2, 11
	s_and_b32 s7, s7, 0x3800
	s_and_b64 s[0:1], s[0:1], exec
	v_and_b32_e32 v64, 64, v67
	s_cselect_b32 s0, s7, 0
	v_add_u32_e32 v64, 64, v64
	v_xor_b32_e32 v68, 1, v67
	v_cmp_lt_i32_e32 vcc, v68, v64
	v_xor_b32_e32 v69, 2, v67
	s_add_i32 s0, s10, s0
	v_cndmask_b32_e32 v68, v67, v68, vcc
	v_cmp_lt_i32_e32 vcc, v69, v64
	v_xor_b32_e32 v70, 4, v67
	s_add_i32 s0, s0, s11
	v_cndmask_b32_e32 v69, v67, v69, vcc
	v_cmp_lt_i32_e32 vcc, v70, v64
	v_xor_b32_e32 v71, 8, v67
	s_ashr_i32 s1, s0, 31
	v_cndmask_b32_e32 v70, v67, v70, vcc
	v_cmp_lt_i32_e32 vcc, v71, v64
	v_xor_b32_e32 v72, 16, v67
	s_lshl_b64 s[0:1], s[0:1], 12
	v_cndmask_b32_e32 v71, v67, v71, vcc
	v_cmp_lt_i32_e32 vcc, v72, v64
	v_xor_b32_e32 v73, 32, v67
	s_add_u32 s8, s15, s0
	v_cndmask_b32_e32 v72, v67, v72, vcc
	v_cmp_lt_i32_e32 vcc, v73, v64
	s_addc_u32 s9, s16, s1
	s_ashr_i32 s7, s6, 31
	v_cndmask_b32_e32 v64, v67, v73, vcc
	s_lshl_b64 s[10:11], s[6:7], 12
	v_lshlrev_b32_e32 v73, 2, v64
	v_and_b32_e32 v64, 63, v66
	s_add_u32 s12, s12, s0
	v_lshlrev_b32_e32 v68, 2, v68
	v_lshlrev_b32_e32 v69, 2, v69
	v_lshlrev_b32_e32 v70, 2, v70
	v_lshlrev_b32_e32 v71, 2, v71
	v_lshlrev_b32_e32 v72, 2, v72
	v_lshlrev_b32_e32 v64, 4, v64
	s_addc_u32 s13, s13, s1
	v_mov_b32_e32 v74, 0x3727c5ac
	s_mov_b32 s7, 0x1da00000
	s_mov_b64 s[22:23], 0x21a00000
	v_lshl_add_u64 v[156:157], s[12:13], 0, v[64:65]
	v_lshl_add_u64 v[156:157], v[156:157], 0, s[22:23]
	global_load_dwordx4 v[140:143], v[156:157], off offset:1024
	global_load_dwordx4 v[144:147], v[156:157], off offset:2048
	global_load_dwordx4 v[148:151], v[156:157], off offset:3072
	global_load_dwordx4 v[152:155], v[156:157], off
	s_waitcnt vmcnt(0)

.LBB0_1472:
	s_add_i32 s4, s6, s8
	s_ashr_i32 s5, s4, 31
	s_lshl_b64 s[0:1], s[4:5], 12
	v_lshl_add_u64 v[64:65], v[152:153], 0, s[0:1]
	global_load_dwordx4 v[88:91], v[64:65], off offset:1024
	global_load_dwordx4 v[98:101], v[64:65], off offset:2048
	global_load_dwordx4 v[66:69], v[64:65], off offset:3072
	global_load_dwordx4 v[102:105], v[64:65], off
	v_mov_b32_e32 v200, v190
	v_mov_b32_e32 v201, v197
	s_mov_b32 s9, 0
	v_mov_b32_e32 v199, 0
	s_waitcnt vmcnt(3)
	v_lshlrev_b32_e32 v84, 16, v90
	s_waitcnt vmcnt(2)
	v_lshlrev_b32_e32 v78, 16, v98
	v_and_b32_e32 v82, 0xffff0000, v98
	v_lshlrev_b32_e32 v76, 16, v99
	v_and_b32_e32 v80, 0xffff0000, v99
	s_waitcnt vmcnt(0)
	v_lshlrev_b32_e32 v93, 16, v102
	v_lshlrev_b32_e32 v92, 16, v104
	v_and_b32_e32 v97, 0xffff0000, v102
	v_and_b32_e32 v96, 0xffff0000, v104
	v_lshlrev_b32_e32 v95, 16, v103
	v_lshlrev_b32_e32 v94, 16, v105
	v_and_b32_e32 v99, 0xffff0000, v103
	v_and_b32_e32 v98, 0xffff0000, v105
	v_and_b32_e32 v85, 0xffff0000, v90
	v_lshlrev_b32_e32 v86, 16, v91
	v_and_b32_e32 v87, 0xffff0000, v91
	v_lshlrev_b32_e32 v72, 16, v66
	v_and_b32_e32 v73, 0xffff0000, v66
	v_lshlrev_b32_e32 v74, 16, v67
	v_and_b32_e32 v75, 0xffff0000, v67
	v_lshlrev_b32_e32 v91, 16, v89
	v_lshlrev_b32_e32 v90, 16, v88
	v_and_b32_e32 v103, 0xffff0000, v89
	v_and_b32_e32 v102, 0xffff0000, v88
	v_pk_add_f32 v[104:105], v[92:93], v[96:97]
	v_pk_add_f32 v[106:107], v[94:95], v[98:99]
	v_lshlrev_b32_e32 v66, 16, v68
	v_and_b32_e32 v70, 0xffff0000, v68
	v_pk_add_f32 v[108:109], v[90:91], v[102:103]
	v_add_f32_e32 v67, v72, v73
	v_add_f32_e32 v71, v74, v75
	v_pk_add_f32 v[104:105], v[104:105], v[106:107]
	v_pk_add_f32 v[106:107], v[108:109], v[108:109] op_sel_hi:[0,1]
	v_pk_add_f32 v[112:113], v[66:67], v[70:71]
	v_add_f32_e32 v67, 0, v105
	v_add_f32_e32 v79, v84, v85
	v_add_f32_e32 v83, v86, v87
	v_mov_b32_e32 v77, v107
	v_add_f32_e32 v81, v104, v67
	v_lshlrev_b32_e32 v89, 16, v101
	v_lshlrev_b32_e32 v88, 16, v100
	v_and_b32_e32 v101, 0xffff0000, v101
	v_and_b32_e32 v100, 0xffff0000, v100
	v_pk_add_f32 v[108:109], v[78:79], v[82:83]
	v_pk_add_f32 v[104:105], v[76:77], v[80:81]
	v_pk_add_f32 v[110:111], v[88:89], v[100:101]
	v_pk_add_f32 v[104:105], v[108:109], v[104:105]
	v_pk_add_f32 v[110:111], v[110:111], v[110:111] op_sel_hi:[0,1]
	v_pk_add_f32 v[104:105], v[104:105], v[104:105] op_sel_hi:[0,1]
	v_lshlrev_b32_e32 v64, 16, v69
	v_and_b32_e32 v68, 0xffff0000, v69
	v_mov_b32_e32 v65, v111
	v_mov_b32_e32 v69, v105
	v_pk_add_f32 v[104:105], v[64:65], v[68:69]
	s_nop 0
	v_pk_add_f32 v[104:105], v[112:113], v[104:105]
	s_nop 0
	v_add_f32_e32 v65, v104, v105
	s_nop 1
	v_add_f32_dpp v65, v65, v65 quad_perm:[1,0,3,2] row_mask:0xf bank_mask:0xf
	s_nop 1
	v_add_f32_dpp v65, v65, v65 quad_perm:[2,3,0,1] row_mask:0xf bank_mask:0xf
	s_nop 1
	v_add_f32_dpp v65, v65, v65 row_half_mirror row_mask:0xf bank_mask:0xf
	s_nop 1
	v_add_f32_dpp v65, v65, v65 row_mirror row_mask:0xf bank_mask:0xf
	s_nop 1
	v_readlane_b32 s98, v65, 0
	v_readlane_b32 s99, v65, 16
	v_readlane_b32 s100, v65, 32
	v_readlane_b32 s101, v65, 48
	s_nop 1
	v_mov_b32_e32 v67, s98
	v_add_f32_e32 v67, s99, v67
	v_mov_b32_e32 v65, s100
	v_add_f32_e32 v65, s101, v65
	v_add_f32_e32 v65, v67, v65
	s_waitcnt lgkmcnt(0)
	v_fmac_f32_e32 v99, 0xba000000, v65
	v_fmac_f32_e32 v97, 0xba000000, v65
	v_fmac_f32_e32 v98, 0xba000000, v65
	v_fmac_f32_e32 v96, 0xba000000, v65
	v_fmac_f32_e32 v102, 0xba000000, v65
	v_fmac_f32_e32 v103, 0xba000000, v65
	v_fmac_f32_e32 v91, 0xba000000, v65
	v_fmac_f32_e32 v95, 0xba000000, v65
	v_fmac_f32_e32 v93, 0xba000000, v65
	v_fmac_f32_e32 v94, 0xba000000, v65
	v_fmac_f32_e32 v92, 0xba000000, v65
	v_fmac_f32_e32 v90, 0xba000000, v65
	v_fmac_f32_e32 v100, 0xba000000, v65
	v_fmac_f32_e32 v101, 0xba000000, v65
	v_fmac_f32_e32 v89, 0xba000000, v65
	v_mov_b32_e32 v106, v97
	v_mov_b32_e32 v107, v96
	v_mov_b32_e32 v110, v99
	v_mov_b32_e32 v111, v98
	v_mov_b32_e32 v112, v91
	v_mov_b32_e32 v113, v103
	v_mov_b32_e32 v91, v102
	v_mov_b32_e32 v104, v93
	v_mov_b32_e32 v105, v92
	v_mov_b32_e32 v108, v95
	v_mov_b32_e32 v109, v94
	v_mov_b32_e32 v116, v89
	v_mov_b32_e32 v117, v101
	v_mov_b32_e32 v89, v100
	v_pk_mul_f32 v[100:101], v[106:107], v[106:107]
	v_pk_mul_f32 v[106:107], v[110:111], v[110:111]
	v_pk_mul_f32 v[110:111], v[112:113], v[112:113]
	v_pk_mul_f32 v[118:119], v[90:91], v[90:91]
	v_fmac_f32_e32 v84, 0xba000000, v65
	v_fmac_f32_e32 v86, 0xba000000, v65
	v_pk_fma_f32 v[100:101], v[104:105], v[104:105], v[100:101]
	v_pk_fma_f32 v[104:105], v[108:109], v[108:109], v[106:107]
	v_pk_mov_b32 v[106:107], v[118:119], v[110:111] op_sel:[1,0]
	v_mov_b32_e32 v119, v111
	v_fmac_f32_e32 v85, 0xba000000, v65
	v_fmac_f32_e32 v87, 0xba000000, v65
	v_mul_f32_e32 v102, v84, v84
	v_mul_f32_e32 v114, v86, v86
	v_pk_add_f32 v[100:101], v[100:101], v[104:105]
	v_pk_add_f32 v[104:105], v[106:107], v[118:119]
	v_fmac_f32_e32 v80, 0xba000000, v65
	v_fmac_f32_e32 v76, 0xba000000, v65
	v_fmac_f32_e32 v82, 0xba000000, v65
	v_fmac_f32_e32 v78, 0xba000000, v65
	v_pk_fma_f32 v[102:103], v[84:85], v[84:85], v[102:103] op_sel_hi:[1,1,0]
	v_pk_fma_f32 v[114:115], v[86:87], v[86:87], v[114:115] op_sel_hi:[1,1,0]
	v_pk_add_f32 v[100:101], v[100:101], v[100:101] op_sel_hi:[0,1]
	v_pk_add_f32 v[104:105], v[104:105], v[104:105] op_sel_hi:[0,1]
	v_mul_f32_e32 v102, v78, v78
	v_mul_f32_e32 v114, v82, v82
	v_mul_f32_e32 v104, v76, v76
	v_mul_f32_e32 v100, v80, v80
	v_pk_add_f32 v[102:103], v[102:103], v[114:115]
	v_pk_add_f32 v[100:101], v[104:105], v[100:101]
	v_fmac_f32_e32 v88, 0xba000000, v65
	v_pk_add_f32 v[100:101], v[102:103], v[100:101]
	v_pk_mul_f32 v[120:121], v[116:117], v[116:117]
	v_pk_mul_f32 v[122:123], v[88:89], v[88:89]
	v_pk_add_f32 v[100:101], v[100:101], v[100:101] op_sel_hi:[0,1]
	v_fmac_f32_e32 v72, 0xba000000, v65
	v_pk_mov_b32 v[108:109], v[122:123], v[120:121] op_sel:[1,0]
	v_mov_b32_e32 v123, v121
	v_fmac_f32_e32 v73, 0xba000000, v65
	v_fmac_f32_e32 v74, 0xba000000, v65
	v_mul_f32_e32 v100, v72, v72
	v_pk_add_f32 v[102:103], v[108:109], v[122:123]
	v_fmac_f32_e32 v75, 0xba000000, v65
	v_pk_fma_f32 v[104:105], v[72:73], v[72:73], v[100:101] op_sel_hi:[1,1,0]
	v_mul_f32_e32 v100, v74, v74
	v_pk_add_f32 v[102:103], v[102:103], v[102:103] op_sel_hi:[0,1]
	v_pk_fma_f32 v[106:107], v[74:75], v[74:75], v[100:101] op_sel_hi:[1,1,0]
	v_fmac_f32_e32 v68, 0xba000000, v65
	v_fmac_f32_e32 v64, 0xba000000, v65
	v_fmac_f32_e32 v70, 0xba000000, v65
	v_fmac_f32_e32 v66, 0xba000000, v65
	v_mul_f32_e32 v104, v66, v66
	v_mul_f32_e32 v106, v70, v70
	v_mul_f32_e32 v102, v64, v64
	v_mul_f32_e32 v100, v68, v68
	v_pk_add_f32 v[104:105], v[104:105], v[106:107]
	v_pk_add_f32 v[100:101], v[102:103], v[100:101]
	v_mov_b32_e32 v102, v92
	v_pk_add_f32 v[100:101], v[104:105], v[100:101]
	v_mov_b32_e32 v103, v96
	v_add_f32_e32 v65, v100, v101
	v_mov_b32_e32 v96, v93
	v_mov_b32_e32 v92, v94
	v_mov_b32_e32 v93, v98
	v_mov_b32_e32 v98, v95
	v_mov_b32_e32 v79, v82
	v_mov_b32_e32 v77, v80
	v_lshl_add_u64 v[100:101], v[154:155], 0, s[0:1]
	s_nop 1
	v_add_f32_dpp v65, v65, v65 quad_perm:[1,0,3,2] row_mask:0xf bank_mask:0xf
	s_nop 1
	v_add_f32_dpp v65, v65, v65 quad_perm:[2,3,0,1] row_mask:0xf bank_mask:0xf
	s_nop 1
	v_add_f32_dpp v65, v65, v65 row_half_mirror row_mask:0xf bank_mask:0xf
	s_nop 1
	v_add_f32_dpp v65, v65, v65 row_mirror row_mask:0xf bank_mask:0xf
	s_nop 1
	v_readlane_b32 s98, v65, 0
	v_readlane_b32 s99, v65, 16
	v_readlane_b32 s100, v65, 32
	v_readlane_b32 s101, v65, 48
	s_nop 1
	v_mov_b32_e32 v67, s98
	v_add_f32_e32 v67, s99, v67
	v_mov_b32_e32 v65, s100
	v_add_f32_e32 v65, s101, v65
	v_add_f32_e32 v65, v67, v65
	s_waitcnt lgkmcnt(0)
	v_fmamk_f32 v65, v65, 0x3a000000, v198
	v_rsq_f32_e32 v104, v65
	v_mov_b32_e32 v67, v70
	v_mov_b32_e32 v65, v68
	v_pk_mul_f32 v[94:95], v[96:97], v[104:105] op_sel_hi:[1,0]
	v_pk_mul_f32 v[96:97], v[98:99], v[104:105] op_sel_hi:[1,0]
	v_pk_mul_f32 v[92:93], v[92:93], v[104:105] op_sel_hi:[1,0]
	v_pk_fma_f32 v[96:97], v[2:3], v[96:97], v[6:7]
	v_pk_fma_f32 v[98:99], v[0:1], v[94:95], v[4:5]
	v_pk_mul_f32 v[94:95], v[102:103], v[104:105] op_sel_hi:[1,0]
	v_pk_fma_f32 v[158:159], v[14:15], v[92:93], v[26:27]
	v_cvt_pk_bf16_f32 v92, v98, v99
	v_cvt_pk_bf16_f32 v93, v96, v97
	v_pk_mul_f32 v[78:79], v[78:79], v[104:105] op_sel_hi:[1,0]
	v_pk_mul_f32 v[76:77], v[76:77], v[104:105] op_sel_hi:[1,0]
	v_pk_fma_f32 v[160:161], v[12:13], v[94:95], v[24:25]
	v_pk_mul_f32 v[90:91], v[90:91], v[104:105] op_sel_hi:[1,0]
	v_cvt_pk_bf16_f32 v94, v160, v161
	v_cvt_pk_bf16_f32 v95, v158, v159
	global_store_dwordx4 v[100:101], v[92:95], off
	v_pk_mul_f32 v[84:85], v[84:85], v[104:105] op_sel_hi:[1,0]
	v_pk_mul_f32 v[86:87], v[86:87], v[104:105] op_sel_hi:[1,0]
	v_pk_mul_f32 v[92:93], v[112:113], v[104:105] op_sel_hi:[1,0]
	v_pk_fma_f32 v[80:81], v[34:35], v[76:77], v[42:43]
	v_pk_fma_f32 v[82:83], v[32:33], v[78:79], v[40:41]
	v_pk_mul_f32 v[76:77], v[88:89], v[104:105] op_sel_hi:[1,0]
	v_pk_mul_f32 v[78:79], v[116:117], v[104:105] op_sel_hi:[1,0]
	v_pk_mul_f32 v[72:73], v[72:73], v[104:105] op_sel_hi:[1,0]
	v_pk_mul_f32 v[74:75], v[74:75], v[104:105] op_sel_hi:[1,0]
	v_pk_mul_f32 v[66:67], v[66:67], v[104:105] op_sel_hi:[1,0]
	v_pk_mul_f32 v[64:65], v[64:65], v[104:105] op_sel_hi:[1,0]
	v_pk_fma_f32 v[92:93], v[18:19], v[92:93], v[30:31]
	v_pk_fma_f32 v[90:91], v[16:17], v[90:91], v[28:29]
	v_pk_fma_f32 v[162:163], v[10:11], v[86:87], v[22:23]
	v_pk_fma_f32 v[164:165], v[8:9], v[84:85], v[20:21]
	v_pk_fma_f32 v[166:167], v[38:39], v[78:79], v[46:47]
	v_pk_fma_f32 v[168:169], v[36:37], v[76:77], v[44:45]
	v_pk_fma_f32 v[74:75], v[50:51], v[74:75], v[58:59]
	v_pk_fma_f32 v[72:73], v[48:49], v[72:73], v[56:57]
	v_pk_fma_f32 v[170:171], v[54:55], v[64:65], v[62:63]
	v_pk_fma_f32 v[172:173], v[52:53], v[66:67], v[60:61]
	v_cvt_pk_bf16_f32 v84, v90, v91
	v_cvt_pk_bf16_f32 v85, v92, v93
	v_cvt_pk_bf16_f32 v86, v164, v165
	v_cvt_pk_bf16_f32 v87, v162, v163
	global_store_dwordx4 v[100:101], v[84:87], off offset:1024
	v_cvt_pk_bf16_f32 v76, v82, v83
	v_cvt_pk_bf16_f32 v77, v80, v81
	v_cvt_pk_bf16_f32 v78, v168, v169
	v_cvt_pk_bf16_f32 v79, v166, v167
	global_store_dwordx4 v[100:101], v[76:79], off offset:2048
	v_cvt_pk_bf16_f32 v64, v72, v73
	v_cvt_pk_bf16_f32 v65, v74, v75
	v_cvt_pk_bf16_f32 v66, v172, v173
	v_cvt_pk_bf16_f32 v67, v170, v171
	v_mov_b32_e32 v174, v98
	v_mov_b32_e32 v175, v160
	v_mov_b32_e32 v160, v99
	v_mov_b32_e32 v176, v96
	v_mov_b32_e32 v177, v158
	v_mov_b32_e32 v158, v97
	v_mov_b32_e32 v178, v90
	v_mov_b32_e32 v179, v164
	v_mov_b32_e32 v164, v91
	v_mov_b32_e32 v180, v92
	v_mov_b32_e32 v181, v162
	v_mov_b32_e32 v162, v93
	v_mov_b32_e32 v182, v82
	v_mov_b32_e32 v183, v168
	v_mov_b32_e32 v168, v83
	v_mov_b32_e32 v184, v80
	v_mov_b32_e32 v185, v166
	v_mov_b32_e32 v166, v81
	v_mov_b32_e32 v186, v72
	v_mov_b32_e32 v187, v172
	v_mov_b32_e32 v172, v73
	v_mov_b32_e32 v188, v74
	v_mov_b32_e32 v189, v170
	v_mov_b32_e32 v170, v75
	global_store_dwordx4 v[100:101], v[64:67], off offset:3072

.LBB0_1892:
	s_cmp_lt_i32 s68, 24
	s_cselect_b64 s[4:5], -1, 0
	s_and_b64 s[0:1], s[4:5], s[0:1]
	s_andn2_b64 vcc, exec, s[0:1]
	s_cbranch_vccnz .LBB0_1896
	s_lshl_b32 s8, s2, 3
	s_and_b32 s0, s34, 7
	s_and_b32 s9, s2, -8
	s_cmp_eq_u32 s0, 0
	s_cselect_b64 s[0:1], -1, 0
	s_movk_i32 s3, 0x800
	s_and_b64 s[6:7], s[0:1], exec
	v_mbcnt_hi_u32_b32 v67, -1, v212
	s_cselect_b32 s3, s3, 0x4000
	s_cselect_b32 s10, s9, s8
	s_add_i32 s6, 0, 0x23fd8
	v_add_u32_e32 v66, s94, v67
	v_mov_b32_e32 v0, s6
	ds_read_b32 v1, v0
	s_add_i32 s6, 0, 0x23fdc
	v_mov_b32_e32 v2, s6
	s_add_i32 s6, 0, 0x23f10
	ds_read_b32 v3, v2
	v_mov_b32_e32 v4, s6
	s_add_i32 s7, 0, 0x23f14
	ds_read_b32 v4, v4
	s_waitcnt lgkmcnt(0)
	v_readfirstlane_b32 s12, v1
	v_mov_b32_e32 v1, s7
	ds_read_b32 v1, v1
	s_add_i32 s7, 0, 0x23f18
	v_readfirstlane_b32 s6, v66
	v_readfirstlane_b32 s13, v3
	v_mov_b32_e32 v3, s7
	s_add_i32 s7, 0, 0x23f1c
	s_ashr_i32 s11, s6, 6
	v_readfirstlane_b32 s6, v4
	v_mov_b32_e32 v4, s7
	ds_read_b32 v3, v3
	ds_read_b32 v4, v4
	ds_read_b32 v0, v0
	s_waitcnt lgkmcnt(0)
	v_readfirstlane_b32 s7, v1
	ds_read_b32 v1, v2
	s_add_i32 s14, s11, s10
	v_readfirstlane_b32 s8, v3
	v_readfirstlane_b32 s9, v4
	v_readfirstlane_b32 s15, v0
	s_cmp_ge_i32 s14, s3
	s_waitcnt lgkmcnt(0)
	v_readfirstlane_b32 s16, v1
	s_cbranch_scc1 .LBB0_1896
	v_lshlrev_b32_e32 v0, 5, v66
	v_and_b32_e32 v64, 0x7e0, v0
	v_mov_b32_e32 v65, 0
	v_lshl_add_u64 v[48:49], s[6:7], 0, v[64:65]
	s_mov_b64 s[6:7], 0x8000
	v_lshl_add_u64 v[56:57], s[8:9], 0, v[64:65]
	v_lshl_add_u64 v[24:25], v[48:49], 0, s[6:7]
	v_lshl_add_u64 v[26:27], v[56:57], 0, s[6:7]
	s_mov_b32 s6, 0x9000
	v_add_co_u32_e32 v58, vcc, s6, v48
	global_load_dwordx4 v[0:3], v[24:25], off offset:2064
	global_load_dwordx4 v[4:7], v[24:25], off offset:16
	global_load_dwordx4 v[8:11], v[24:25], off offset:2048
	global_load_dwordx4 v[12:15], v[26:27], off offset:2064
	global_load_dwordx4 v[16:19], v[26:27], off offset:16
	global_load_dwordx4 v[20:23], v[26:27], off offset:2048
	v_addc_co_u32_e32 v59, vcc, 0, v49, vcc
	v_add_co_u32_e32 v68, vcc, s6, v56
	s_mov_b64 s[6:7], 0x9000
	s_nop 0
	v_addc_co_u32_e32 v69, vcc, 0, v57, vcc
	v_lshl_add_u64 v[36:37], v[48:49], 0, s[6:7]
	v_lshl_add_u64 v[50:51], v[56:57], 0, s[6:7]
	s_mov_b64 s[6:7], 0x9800
	global_load_dwordx4 v[24:27], v[58:59], off offset:-4096
	global_load_dwordx4 v[28:31], v[58:59], off
	global_load_dwordx4 v[32:35], v[36:37], off offset:16
	s_nop 0
	global_load_dwordx4 v[36:39], v[68:69], off offset:-4096
	global_load_dwordx4 v[40:43], v[68:69], off
	global_load_dwordx4 v[44:47], v[50:51], off offset:16
	v_lshl_add_u64 v[60:61], v[48:49], 0, s[6:7]
	global_load_dwordx4 v[48:51], v[58:59], off offset:2048
	global_load_dwordx4 v[52:55], v[60:61], off offset:16
	v_lshl_add_u64 v[70:71], v[56:57], 0, s[6:7]
	global_load_dwordx4 v[56:59], v[68:69], off offset:2048
	global_load_dwordx4 v[60:63], v[70:71], off offset:16
	s_lshl_b32 s8, s34, 3
	s_and_b64 s[6:7], s[0:1], exec
	s_cselect_b32 s6, s34, s8
	s_lshl_b32 s7, s2, 11
	s_and_b32 s7, s7, 0x3800
	s_and_b64 s[0:1], s[0:1], exec
	v_and_b32_e32 v64, 64, v67
	s_cselect_b32 s0, s7, 0
	v_add_u32_e32 v64, 64, v64
	v_xor_b32_e32 v68, 1, v67
	v_cmp_lt_i32_e32 vcc, v68, v64
	v_xor_b32_e32 v69, 2, v67
	s_add_i32 s0, s10, s0
	v_cndmask_b32_e32 v68, v67, v68, vcc
	v_cmp_lt_i32_e32 vcc, v69, v64
	v_xor_b32_e32 v70, 4, v67
	s_add_i32 s0, s0, s11
	v_cndmask_b32_e32 v69, v67, v69, vcc
	v_cmp_lt_i32_e32 vcc, v70, v64
	v_xor_b32_e32 v71, 8, v67
	s_ashr_i32 s1, s0, 31
	v_cndmask_b32_e32 v70, v67, v70, vcc
	v_cmp_lt_i32_e32 vcc, v71, v64
	v_xor_b32_e32 v72, 16, v67
	s_lshl_b64 s[0:1], s[0:1], 12
	v_cndmask_b32_e32 v71, v67, v71, vcc
	v_cmp_lt_i32_e32 vcc, v72, v64
	v_xor_b32_e32 v73, 32, v67
	s_add_u32 s8, s15, s0
	v_cndmask_b32_e32 v72, v67, v72, vcc
	v_cmp_lt_i32_e32 vcc, v73, v64
	s_addc_u32 s9, s16, s1
	s_ashr_i32 s7, s6, 31
	v_cndmask_b32_e32 v64, v67, v73, vcc
	s_lshl_b64 s[10:11], s[6:7], 12
	v_lshlrev_b32_e32 v73, 2, v64
	v_and_b32_e32 v64, 63, v66
	s_add_u32 s12, s12, s0
	v_lshlrev_b32_e32 v68, 2, v68
	v_lshlrev_b32_e32 v69, 2, v69
	v_lshlrev_b32_e32 v70, 2, v70
	v_lshlrev_b32_e32 v71, 2, v71
	v_lshlrev_b32_e32 v72, 2, v72
	v_lshlrev_b32_e32 v64, 4, v64
	s_addc_u32 s13, s13, s1
	v_mov_b32_e32 v74, 0x3727c5ac
	s_mov_b32 s7, 0x1da00000
	s_mov_b64 s[22:23], 0x21a00000
	v_lshl_add_u64 v[156:157], s[12:13], 0, v[64:65]
	v_lshl_add_u64 v[156:157], v[156:157], 0, s[22:23]
	global_load_dwordx4 v[140:143], v[156:157], off offset:1024
	global_load_dwordx4 v[144:147], v[156:157], off offset:2048
	global_load_dwordx4 v[148:151], v[156:157], off offset:3072
	global_load_dwordx4 v[152:155], v[156:157], off
	s_waitcnt vmcnt(0)

.LBB0_2106:
	s_cmp_lt_i32 s68, 27
	s_cselect_b64 s[4:5], -1, 0
	s_and_b64 s[0:1], s[4:5], s[0:1]
	s_andn2_b64 vcc, exec, s[0:1]
	s_cbranch_vccnz .LBB0_2110
	s_lshl_b32 s8, s2, 3
	s_and_b32 s0, s34, 7
	s_and_b32 s9, s2, -8
	s_cmp_eq_u32 s0, 0
	s_cselect_b64 s[0:1], -1, 0
	s_movk_i32 s3, 0x800
	s_and_b64 s[6:7], s[0:1], exec
	v_mbcnt_hi_u32_b32 v67, -1, v212
	s_cselect_b32 s3, s3, 0x4000
	s_cselect_b32 s10, s9, s8
	s_add_i32 s6, 0, 0x23fd8
	v_add_u32_e32 v66, s94, v67
	v_mov_b32_e32 v0, s6
	ds_read_b32 v1, v0
	s_add_i32 s6, 0, 0x23fdc
	v_mov_b32_e32 v2, s6
	s_add_i32 s6, 0, 0x23f10
	ds_read_b32 v3, v2
	v_mov_b32_e32 v4, s6
	s_add_i32 s7, 0, 0x23f14
	ds_read_b32 v4, v4
	s_waitcnt lgkmcnt(0)
	v_readfirstlane_b32 s12, v1
	v_mov_b32_e32 v1, s7
	ds_read_b32 v1, v1
	s_add_i32 s7, 0, 0x23f18
	v_readfirstlane_b32 s6, v66
	v_readfirstlane_b32 s13, v3
	v_mov_b32_e32 v3, s7
	s_add_i32 s7, 0, 0x23f1c
	s_ashr_i32 s11, s6, 6
	v_readfirstlane_b32 s6, v4
	v_mov_b32_e32 v4, s7
	ds_read_b32 v3, v3
	ds_read_b32 v4, v4
	ds_read_b32 v0, v0
	s_waitcnt lgkmcnt(0)
	v_readfirstlane_b32 s7, v1
	ds_read_b32 v1, v2
	s_add_i32 s14, s11, s10
	v_readfirstlane_b32 s8, v3
	v_readfirstlane_b32 s9, v4
	v_readfirstlane_b32 s15, v0
	s_cmp_ge_i32 s14, s3
	s_waitcnt lgkmcnt(0)
	v_readfirstlane_b32 s16, v1
	s_cbranch_scc1 .LBB0_2110
	v_lshlrev_b32_e32 v0, 5, v66
	v_and_b32_e32 v64, 0x7e0, v0
	v_mov_b32_e32 v65, 0
	v_lshl_add_u64 v[48:49], s[6:7], 0, v[64:65]
	s_mov_b64 s[6:7], 0xa000
	v_lshl_add_u64 v[56:57], s[8:9], 0, v[64:65]
	v_lshl_add_u64 v[24:25], v[48:49], 0, s[6:7]
	v_lshl_add_u64 v[26:27], v[56:57], 0, s[6:7]
	s_mov_b32 s6, 0xb000
	v_add_co_u32_e32 v58, vcc, s6, v48
	global_load_dwordx4 v[0:3], v[24:25], off offset:2064
	global_load_dwordx4 v[4:7], v[24:25], off offset:16
	global_load_dwordx4 v[8:11], v[24:25], off offset:2048
	global_load_dwordx4 v[12:15], v[26:27], off offset:2064
	global_load_dwordx4 v[16:19], v[26:27], off offset:16
	global_load_dwordx4 v[20:23], v[26:27], off offset:2048
	v_addc_co_u32_e32 v59, vcc, 0, v49, vcc
	v_add_co_u32_e32 v68, vcc, s6, v56
	s_mov_b64 s[6:7], 0xb000
	s_nop 0
	v_addc_co_u32_e32 v69, vcc, 0, v57, vcc
	v_lshl_add_u64 v[36:37], v[48:49], 0, s[6:7]
	v_lshl_add_u64 v[50:51], v[56:57], 0, s[6:7]
	s_mov_b64 s[6:7], 0xb800
	global_load_dwordx4 v[24:27], v[58:59], off offset:-4096
	global_load_dwordx4 v[28:31], v[58:59], off
	global_load_dwordx4 v[32:35], v[36:37], off offset:16
	s_nop 0
	global_load_dwordx4 v[36:39], v[68:69], off offset:-4096
	global_load_dwordx4 v[40:43], v[68:69], off
	global_load_dwordx4 v[44:47], v[50:51], off offset:16
	v_lshl_add_u64 v[60:61], v[48:49], 0, s[6:7]
	global_load_dwordx4 v[48:51], v[58:59], off offset:2048
	global_load_dwordx4 v[52:55], v[60:61], off offset:16
	v_lshl_add_u64 v[70:71], v[56:57], 0, s[6:7]
	global_load_dwordx4 v[56:59], v[68:69], off offset:2048
	global_load_dwordx4 v[60:63], v[70:71], off offset:16
	s_lshl_b32 s8, s34, 3
	s_and_b64 s[6:7], s[0:1], exec
	s_cselect_b32 s6, s34, s8
	s_lshl_b32 s7, s2, 11
	s_and_b32 s7, s7, 0x3800
	s_and_b64 s[0:1], s[0:1], exec
	v_and_b32_e32 v64, 64, v67
	s_cselect_b32 s0, s7, 0
	v_add_u32_e32 v64, 64, v64
	v_xor_b32_e32 v68, 1, v67
	v_cmp_lt_i32_e32 vcc, v68, v64
	v_xor_b32_e32 v69, 2, v67
	s_add_i32 s0, s10, s0
	v_cndmask_b32_e32 v68, v67, v68, vcc
	v_cmp_lt_i32_e32 vcc, v69, v64
	v_xor_b32_e32 v70, 4, v67
	s_add_i32 s0, s0, s11
	v_cndmask_b32_e32 v69, v67, v69, vcc
	v_cmp_lt_i32_e32 vcc, v70, v64
	v_xor_b32_e32 v71, 8, v67
	s_ashr_i32 s1, s0, 31
	v_cndmask_b32_e32 v70, v67, v70, vcc
	v_cmp_lt_i32_e32 vcc, v71, v64
	v_xor_b32_e32 v72, 16, v67
	s_lshl_b64 s[0:1], s[0:1], 12
	v_cndmask_b32_e32 v71, v67, v71, vcc
	v_cmp_lt_i32_e32 vcc, v72, v64
	v_xor_b32_e32 v73, 32, v67
	s_add_u32 s8, s15, s0
	v_cndmask_b32_e32 v72, v67, v72, vcc
	v_cmp_lt_i32_e32 vcc, v73, v64
	s_addc_u32 s9, s16, s1
	s_ashr_i32 s7, s6, 31
	v_cndmask_b32_e32 v64, v67, v73, vcc
	s_lshl_b64 s[10:11], s[6:7], 12
	v_lshlrev_b32_e32 v73, 2, v64
	v_and_b32_e32 v64, 63, v66
	s_add_u32 s12, s12, s0
	v_lshlrev_b32_e32 v68, 2, v68
	v_lshlrev_b32_e32 v69, 2, v69
	v_lshlrev_b32_e32 v70, 2, v70
	v_lshlrev_b32_e32 v71, 2, v71
	v_lshlrev_b32_e32 v72, 2, v72
	v_lshlrev_b32_e32 v64, 4, v64
	s_addc_u32 s13, s13, s1
	v_mov_b32_e32 v74, 0x3727c5ac
	s_mov_b32 s7, 0x1da00000
	s_mov_b64 s[22:23], 0x21a00000
	v_lshl_add_u64 v[156:157], s[12:13], 0, v[64:65]
	v_lshl_add_u64 v[156:157], v[156:157], 0, s[22:23]
	global_load_dwordx4 v[140:143], v[156:157], off offset:1024
	global_load_dwordx4 v[144:147], v[156:157], off offset:2048
	global_load_dwordx4 v[148:151], v[156:157], off offset:3072
	global_load_dwordx4 v[152:155], v[156:157], off
	s_waitcnt vmcnt(0)
